# v29 without the relaxed first-iteration waits in G5 (standard waits everywhere): rsq row norms, attention K-fragment ring + counted PV waits, early GEMM hand-off barrier with priority tail, peeled Src
# baseline (speedup 1.0000x reference)
.LBB0_1797:
	s_ashr_i32 s19, s18, 31
	s_lshl_b64 s[20:21], s[18:19], 20
	v_readlane_b32 s5, v243, 17
	s_add_u32 s28, s5, s20
	v_readlane_b32 s5, v243, 18
	s_addc_u32 s29, s5, s21
	s_and_b64 s[20:21], s[34:35], exec
	s_cselect_b32 s11, s29, s23
	s_cselect_b32 s13, s28, s22
	s_ashr_i32 s5, s4, 31
	s_lshl_b64 s[20:21], s[4:5], 20
	s_add_u32 s38, s25, s20
	s_addc_u32 s39, s27, s21
	s_and_b64 s[20:21], s[34:35], exec
	s_cselect_b32 s5, s39, s41
	s_cselect_b32 s19, s38, s40
	s_add_u32 s22, s22, 0x80080
	s_addc_u32 s23, s23, 0
	s_add_u32 s20, s40, 0x100
	s_addc_u32 s21, s41, 0
	s_mov_b32 s26, -2
	s_add_u32 s40, s22, 0xfff80080
	s_addc_u32 s41, s23, -1
	s_add_i32 s52, 0, 0x10000
	s_cmp_eq_u32 s26, 28
	s_cselect_b32 s43, s11, s41
	s_cselect_b32 s42, s13, s40
	v_add_u32_e32 v147, s52, v141
	s_cselect_b32 s41, s5, s21
	s_cselect_b32 s40, s19, s20
	s_add_i32 s54, 0, 0x14000
	ds_read_b128 v[152:155], v147
	ds_read_b128 v[164:167], v147 offset:1024
	ds_read_b128 v[180:183], v147 offset:2048
	ds_read_b128 v[184:187], v147 offset:3072
	v_add_u32_e32 v147, s54, v141
	ds_read_b128 v[188:191], v147
	ds_read_b128 v[192:195], v147 offset:1024
	ds_read_b128 v[196:199], v147 offset:2048
	ds_read_b128 v[200:203], v147 offset:3072
	v_lshl_add_u64 v[160:161], s[22:23], 0, v[136:137]
	s_add_i32 m0, s45, 0xc000
	ds_read_b128 v[204:207], v145
	ds_read_b128 v[208:211], v145 offset:1024
	ds_read_b128 v[212:215], v145 offset:2048
	ds_read_b128 v[216:219], v145 offset:3072
	ds_read_b128 v[220:223], v145 offset:4096
	ds_read_b128 v[224:227], v145 offset:5120
	ds_read_b128 v[228:231], v145 offset:6144
	ds_read_b128 v[232:235], v145 offset:7168
	global_load_lds_dwordx4 v[160:161], off
	v_lshl_add_u64 v[160:161], s[22:23], 0, v[138:139]
	s_add_i32 m0, s45, 0xe000
	s_nop 0
	global_load_lds_dwordx4 v[160:161], off
	s_waitcnt vmcnt(8)
	s_waitcnt lgkmcnt(0)
	s_barrier
	s_setprio 1
	s_waitcnt lgkmcnt(0)
	v_mfma_f32_16x16x32_bf16 v[126:129], v[152:155], v[204:207], 0
	v_mfma_f32_16x16x32_bf16 v[122:125], v[180:183], v[204:207], 0
	v_mfma_f32_16x16x32_bf16 v[110:113], v[152:155], v[212:215], 0
	v_mfma_f32_16x16x32_bf16 v[106:109], v[180:183], v[212:215], 0
	v_mfma_f32_16x16x32_bf16 v[94:97], v[152:155], v[220:223], 0
	v_mfma_f32_16x16x32_bf16 v[90:93], v[180:183], v[220:223], 0
	v_mfma_f32_16x16x32_bf16 v[78:81], v[152:155], v[228:231], 0
	v_mfma_f32_16x16x32_bf16 v[74:77], v[180:183], v[228:231], 0
	v_mfma_f32_16x16x32_bf16 v[126:129], v[164:167], v[208:211], v[126:129]
	v_mfma_f32_16x16x32_bf16 v[122:125], v[184:187], v[208:211], v[122:125]
	v_mfma_f32_16x16x32_bf16 v[110:113], v[164:167], v[216:219], v[110:113]
	v_mfma_f32_16x16x32_bf16 v[106:109], v[184:187], v[216:219], v[106:109]
	v_mfma_f32_16x16x32_bf16 v[94:97], v[164:167], v[224:227], v[94:97]
	v_mfma_f32_16x16x32_bf16 v[90:93], v[184:187], v[224:227], v[90:93]
	v_mfma_f32_16x16x32_bf16 v[78:81], v[164:167], v[232:235], v[78:81]
	v_mfma_f32_16x16x32_bf16 v[74:77], v[184:187], v[232:235], v[74:77]
	s_setprio 0
	s_setprio 1
	v_mfma_f32_16x16x32_bf16 v[118:121], v[188:191], v[204:207], 0
	v_mfma_f32_16x16x32_bf16 v[114:117], v[196:199], v[204:207], 0
	v_mfma_f32_16x16x32_bf16 v[102:105], v[188:191], v[212:215], 0
	v_mfma_f32_16x16x32_bf16 v[98:101], v[196:199], v[212:215], 0
	v_mfma_f32_16x16x32_bf16 v[86:89], v[188:191], v[220:223], 0
	v_mfma_f32_16x16x32_bf16 v[82:85], v[196:199], v[220:223], 0
	v_mfma_f32_16x16x32_bf16 v[70:73], v[188:191], v[228:231], 0
	v_mfma_f32_16x16x32_bf16 v[66:69], v[196:199], v[228:231], 0
	v_mfma_f32_16x16x32_bf16 v[118:121], v[192:195], v[208:211], v[118:121]
	v_mfma_f32_16x16x32_bf16 v[114:117], v[200:203], v[208:211], v[114:117]
	v_mfma_f32_16x16x32_bf16 v[102:105], v[192:195], v[216:219], v[102:105]
	v_mfma_f32_16x16x32_bf16 v[98:101], v[200:203], v[216:219], v[98:101]
	v_mfma_f32_16x16x32_bf16 v[86:89], v[192:195], v[224:227], v[86:89]
	v_mfma_f32_16x16x32_bf16 v[82:85], v[200:203], v[224:227], v[82:85]
	s_setprio 2
	s_barrier
	v_mfma_f32_16x16x32_bf16 v[70:73], v[192:195], v[232:235], v[70:73]
	v_mfma_f32_16x16x32_bf16 v[66:69], v[200:203], v[232:235], v[66:69]
	s_setprio 0
	s_add_i32 s52, s52, s44
	v_lshl_add_u64 v[160:161], s[40:41], 0, v[162:163]
	s_mov_b32 m0, s52
	ds_read_b128 v[204:207], v145 offset:16384
	ds_read_b128 v[208:211], v145 offset:17408
	ds_read_b128 v[212:215], v145 offset:18432
	ds_read_b128 v[216:219], v145 offset:19456
	ds_read_b128 v[220:223], v145 offset:20480
	ds_read_b128 v[224:227], v145 offset:21504
	ds_read_b128 v[228:231], v145 offset:22528
	ds_read_b128 v[232:235], v145 offset:23552
	global_load_lds_dwordx4 v[160:161], off
	s_add_i32 m0, s52, 0x2000
	s_add_u32 s52, s40, 0x80000
	v_lshl_add_u64 v[168:169], s[40:41], 0, v[130:131]
	s_addc_u32 s53, s41, 0
	s_add_i32 s54, s54, s44
	global_load_lds_dwordx4 v[168:169], off
	v_lshl_add_u64 v[236:237], s[52:53], 0, v[162:163]
	s_mov_b32 m0, s54
	v_lshl_add_u64 v[238:239], s[42:43], 0, v[132:133]
	global_load_lds_dwordx4 v[236:237], off
	v_lshl_add_u64 v[236:237], s[52:53], 0, v[130:131]
	s_add_i32 m0, s54, 0x2000
	s_nop 0
	global_load_lds_dwordx4 v[236:237], off
	v_lshl_add_u64 v[236:237], s[42:43], 0, v[134:135]
	s_mov_b32 m0, s45
	s_nop 0
	global_load_lds_dwordx4 v[236:237], off
	s_mov_b32 m0, s46
	s_nop 0
	global_load_lds_dwordx4 v[238:239], off
	s_waitcnt vmcnt(8)
	s_waitcnt lgkmcnt(0)
	s_barrier
	s_setprio 1
	s_waitcnt lgkmcnt(0)
	v_mfma_f32_16x16x32_bf16 v[62:65], v[152:155], v[204:207], 0
	v_mfma_f32_16x16x32_bf16 v[58:61], v[180:183], v[204:207], 0
	v_mfma_f32_16x16x32_bf16 v[46:49], v[152:155], v[212:215], 0
	v_mfma_f32_16x16x32_bf16 v[42:45], v[180:183], v[212:215], 0
	v_mfma_f32_16x16x32_bf16 v[30:33], v[152:155], v[220:223], 0
	v_mfma_f32_16x16x32_bf16 v[26:29], v[180:183], v[220:223], 0
	v_mfma_f32_16x16x32_bf16 v[14:17], v[152:155], v[228:231], 0
	v_mfma_f32_16x16x32_bf16 v[10:13], v[180:183], v[228:231], 0
	v_mfma_f32_16x16x32_bf16 v[62:65], v[164:167], v[208:211], v[62:65]
	v_mfma_f32_16x16x32_bf16 v[58:61], v[184:187], v[208:211], v[58:61]
	v_mfma_f32_16x16x32_bf16 v[46:49], v[164:167], v[216:219], v[46:49]
	v_mfma_f32_16x16x32_bf16 v[42:45], v[184:187], v[216:219], v[42:45]
	v_mfma_f32_16x16x32_bf16 v[30:33], v[164:167], v[224:227], v[30:33]
	v_mfma_f32_16x16x32_bf16 v[26:29], v[184:187], v[224:227], v[26:29]
	v_mfma_f32_16x16x32_bf16 v[14:17], v[164:167], v[232:235], v[14:17]
	v_mfma_f32_16x16x32_bf16 v[10:13], v[184:187], v[232:235], v[10:13]
	s_setprio 0
	s_setprio 1
	v_mfma_f32_16x16x32_bf16 v[54:57], v[188:191], v[204:207], 0
	v_mfma_f32_16x16x32_bf16 v[50:53], v[196:199], v[204:207], 0
	v_mfma_f32_16x16x32_bf16 v[38:41], v[188:191], v[212:215], 0
	v_mfma_f32_16x16x32_bf16 v[34:37], v[196:199], v[212:215], 0
	v_mfma_f32_16x16x32_bf16 v[22:25], v[188:191], v[220:223], 0
	v_mfma_f32_16x16x32_bf16 v[18:21], v[196:199], v[220:223], 0
	v_mfma_f32_16x16x32_bf16 v[6:9], v[188:191], v[228:231], 0
	v_mfma_f32_16x16x32_bf16 v[2:5], v[196:199], v[228:231], 0
	v_mfma_f32_16x16x32_bf16 v[54:57], v[192:195], v[208:211], v[54:57]
	v_mfma_f32_16x16x32_bf16 v[50:53], v[200:203], v[208:211], v[50:53]
	v_mfma_f32_16x16x32_bf16 v[38:41], v[192:195], v[216:219], v[38:41]
	v_mfma_f32_16x16x32_bf16 v[34:37], v[200:203], v[216:219], v[34:37]
	v_mfma_f32_16x16x32_bf16 v[22:25], v[192:195], v[224:227], v[22:25]
	v_mfma_f32_16x16x32_bf16 v[18:21], v[200:203], v[224:227], v[18:21]
	s_setprio 2
	s_barrier
	v_mfma_f32_16x16x32_bf16 v[6:9], v[192:195], v[232:235], v[6:9]
	v_mfma_f32_16x16x32_bf16 v[2:5], v[200:203], v[232:235], v[2:5]
	s_setprio 0
	s_add_i32 s52, 0, 0x18000
	v_add_u32_e32 v147, s52, v141
	s_add_i32 s53, 0, 0x1c000
	ds_read_b128 v[152:155], v147
	ds_read_b128 v[164:167], v147 offset:1024
	ds_read_b128 v[180:183], v147 offset:2048
	ds_read_b128 v[184:187], v147 offset:3072
	v_add_u32_e32 v147, s53, v141
	ds_read_b128 v[188:191], v147
	ds_read_b128 v[192:195], v147 offset:1024
	ds_read_b128 v[196:199], v147 offset:2048
	ds_read_b128 v[200:203], v147 offset:3072
	s_add_u32 s42, s42, 0x80000
	s_addc_u32 s43, s43, 0
	s_mov_b32 m0, s47
	v_lshl_add_u64 v[240:241], s[42:43], 0, v[134:135]
	ds_read_b128 v[204:207], v145 offset:32768
	ds_read_b128 v[208:211], v145 offset:33792
	ds_read_b128 v[212:215], v145 offset:34816
	ds_read_b128 v[216:219], v145 offset:35840
	ds_read_b128 v[220:223], v145 offset:36864
	ds_read_b128 v[224:227], v145 offset:37888
	ds_read_b128 v[228:231], v145 offset:38912
	ds_read_b128 v[232:235], v145 offset:39936
	global_load_lds_dwordx4 v[240:241], off
	v_lshl_add_u64 v[240:241], s[42:43], 0, v[132:133]
	s_mov_b32 m0, s48
	s_nop 0
	global_load_lds_dwordx4 v[240:241], off
	s_waitcnt vmcnt(8)
	s_waitcnt lgkmcnt(0)
	s_barrier
	s_setprio 1
	s_waitcnt lgkmcnt(0)
	v_mfma_f32_16x16x32_bf16 v[126:129], v[152:155], v[204:207], v[126:129]
	v_mfma_f32_16x16x32_bf16 v[122:125], v[180:183], v[204:207], v[122:125]
	v_mfma_f32_16x16x32_bf16 v[110:113], v[152:155], v[212:215], v[110:113]
	v_mfma_f32_16x16x32_bf16 v[106:109], v[180:183], v[212:215], v[106:109]
	v_mfma_f32_16x16x32_bf16 v[94:97], v[152:155], v[220:223], v[94:97]
	v_mfma_f32_16x16x32_bf16 v[90:93], v[180:183], v[220:223], v[90:93]
	v_mfma_f32_16x16x32_bf16 v[78:81], v[152:155], v[228:231], v[78:81]
	v_mfma_f32_16x16x32_bf16 v[74:77], v[180:183], v[228:231], v[74:77]
	v_mfma_f32_16x16x32_bf16 v[126:129], v[164:167], v[208:211], v[126:129]
	v_mfma_f32_16x16x32_bf16 v[122:125], v[184:187], v[208:211], v[122:125]
	v_mfma_f32_16x16x32_bf16 v[110:113], v[164:167], v[216:219], v[110:113]
	v_mfma_f32_16x16x32_bf16 v[106:109], v[184:187], v[216:219], v[106:109]
	v_mfma_f32_16x16x32_bf16 v[94:97], v[164:167], v[224:227], v[94:97]
	v_mfma_f32_16x16x32_bf16 v[90:93], v[184:187], v[224:227], v[90:93]
	v_mfma_f32_16x16x32_bf16 v[78:81], v[164:167], v[232:235], v[78:81]
	v_mfma_f32_16x16x32_bf16 v[74:77], v[184:187], v[232:235], v[74:77]
	s_setprio 0
	s_setprio 1
	v_mfma_f32_16x16x32_bf16 v[118:121], v[188:191], v[204:207], v[118:121]
	v_mfma_f32_16x16x32_bf16 v[114:117], v[196:199], v[204:207], v[114:117]
	v_mfma_f32_16x16x32_bf16 v[102:105], v[188:191], v[212:215], v[102:105]
	v_mfma_f32_16x16x32_bf16 v[98:101], v[196:199], v[212:215], v[98:101]
	v_mfma_f32_16x16x32_bf16 v[86:89], v[188:191], v[220:223], v[86:89]
	v_mfma_f32_16x16x32_bf16 v[82:85], v[196:199], v[220:223], v[82:85]
	v_mfma_f32_16x16x32_bf16 v[70:73], v[188:191], v[228:231], v[70:73]
	v_mfma_f32_16x16x32_bf16 v[66:69], v[196:199], v[228:231], v[66:69]
	v_mfma_f32_16x16x32_bf16 v[118:121], v[192:195], v[208:211], v[118:121]
	v_mfma_f32_16x16x32_bf16 v[114:117], v[200:203], v[208:211], v[114:117]
	v_mfma_f32_16x16x32_bf16 v[102:105], v[192:195], v[216:219], v[102:105]
	v_mfma_f32_16x16x32_bf16 v[98:101], v[200:203], v[216:219], v[98:101]
	v_mfma_f32_16x16x32_bf16 v[86:89], v[192:195], v[224:227], v[86:89]
	v_mfma_f32_16x16x32_bf16 v[82:85], v[200:203], v[224:227], v[82:85]
	s_setprio 2
	s_barrier
	v_mfma_f32_16x16x32_bf16 v[70:73], v[192:195], v[232:235], v[70:73]
	v_mfma_f32_16x16x32_bf16 v[66:69], v[200:203], v[232:235], v[66:69]
	s_setprio 0
	s_add_i32 s42, s52, s44
	v_lshl_add_u64 v[160:161], v[160:161], 0, s[6:7]
	s_mov_b32 m0, s42
	ds_read_b128 v[204:207], v145 offset:49152
	ds_read_b128 v[208:211], v145 offset:50176
	ds_read_b128 v[212:215], v145 offset:51200
	ds_read_b128 v[216:219], v145 offset:52224
	ds_read_b128 v[220:223], v145 offset:53248
	ds_read_b128 v[224:227], v145 offset:54272
	ds_read_b128 v[228:231], v145 offset:55296
	ds_read_b128 v[232:235], v145 offset:56320
	global_load_lds_dwordx4 v[160:161], off
	s_add_i32 m0, s42, 0x2000
	s_add_u32 s40, s40, 0x80080
	v_lshl_add_u64 v[160:161], v[168:169], 0, s[6:7]
	s_addc_u32 s41, s41, 0
	s_add_i32 s42, s53, s44
	global_load_lds_dwordx4 v[160:161], off
	v_lshl_add_u64 v[160:161], s[40:41], 0, v[162:163]
	s_mov_b32 m0, s42
	s_nop 0
	global_load_lds_dwordx4 v[160:161], off
	v_lshl_add_u64 v[160:161], s[40:41], 0, v[130:131]
	s_add_i32 m0, s42, 0x2000
	s_nop 0
	global_load_lds_dwordx4 v[160:161], off
	v_lshl_add_u64 v[160:161], v[236:237], 0, s[6:7]
	s_mov_b32 m0, s49
	s_nop 0
	global_load_lds_dwordx4 v[160:161], off
	v_lshl_add_u64 v[160:161], v[238:239], 0, s[6:7]
	s_mov_b32 m0, s50
	s_nop 0
	global_load_lds_dwordx4 v[160:161], off
	s_waitcnt vmcnt(8)
	s_waitcnt lgkmcnt(0)
	s_barrier
	s_setprio 1
	s_waitcnt lgkmcnt(0)
	v_mfma_f32_16x16x32_bf16 v[62:65], v[152:155], v[204:207], v[62:65]
	v_mfma_f32_16x16x32_bf16 v[58:61], v[180:183], v[204:207], v[58:61]
	v_mfma_f32_16x16x32_bf16 v[46:49], v[152:155], v[212:215], v[46:49]
	v_mfma_f32_16x16x32_bf16 v[42:45], v[180:183], v[212:215], v[42:45]
	v_mfma_f32_16x16x32_bf16 v[30:33], v[152:155], v[220:223], v[30:33]
	v_mfma_f32_16x16x32_bf16 v[26:29], v[180:183], v[220:223], v[26:29]
	v_mfma_f32_16x16x32_bf16 v[14:17], v[152:155], v[228:231], v[14:17]
	v_mfma_f32_16x16x32_bf16 v[10:13], v[180:183], v[228:231], v[10:13]
	v_mfma_f32_16x16x32_bf16 v[62:65], v[164:167], v[208:211], v[62:65]
	v_mfma_f32_16x16x32_bf16 v[58:61], v[184:187], v[208:211], v[58:61]
	v_mfma_f32_16x16x32_bf16 v[46:49], v[164:167], v[216:219], v[46:49]
	v_mfma_f32_16x16x32_bf16 v[42:45], v[184:187], v[216:219], v[42:45]
	v_mfma_f32_16x16x32_bf16 v[30:33], v[164:167], v[224:227], v[30:33]
	v_mfma_f32_16x16x32_bf16 v[26:29], v[184:187], v[224:227], v[26:29]
	v_mfma_f32_16x16x32_bf16 v[14:17], v[164:167], v[232:235], v[14:17]
	v_mfma_f32_16x16x32_bf16 v[10:13], v[184:187], v[232:235], v[10:13]
	s_setprio 0
	s_setprio 1
	v_mfma_f32_16x16x32_bf16 v[54:57], v[188:191], v[204:207], v[54:57]
	v_mfma_f32_16x16x32_bf16 v[50:53], v[196:199], v[204:207], v[50:53]
	v_mfma_f32_16x16x32_bf16 v[38:41], v[188:191], v[212:215], v[38:41]
	v_mfma_f32_16x16x32_bf16 v[34:37], v[196:199], v[212:215], v[34:37]
	v_mfma_f32_16x16x32_bf16 v[22:25], v[188:191], v[220:223], v[22:25]
	v_mfma_f32_16x16x32_bf16 v[18:21], v[196:199], v[220:223], v[18:21]
	v_mfma_f32_16x16x32_bf16 v[6:9], v[188:191], v[228:231], v[6:9]
	v_mfma_f32_16x16x32_bf16 v[2:5], v[196:199], v[228:231], v[2:5]
	v_mfma_f32_16x16x32_bf16 v[54:57], v[192:195], v[208:211], v[54:57]
	v_mfma_f32_16x16x32_bf16 v[50:53], v[200:203], v[208:211], v[50:53]
	v_mfma_f32_16x16x32_bf16 v[38:41], v[192:195], v[216:219], v[38:41]
	v_mfma_f32_16x16x32_bf16 v[34:37], v[200:203], v[216:219], v[34:37]
	v_mfma_f32_16x16x32_bf16 v[22:25], v[192:195], v[224:227], v[22:25]
	v_mfma_f32_16x16x32_bf16 v[18:21], v[200:203], v[224:227], v[18:21]
	s_setprio 2
	s_barrier
	v_mfma_f32_16x16x32_bf16 v[6:9], v[192:195], v[232:235], v[6:9]
	v_mfma_f32_16x16x32_bf16 v[2:5], v[200:203], v[232:235], v[2:5]
	s_setprio 0
	s_add_i32 s26, s26, 2
	s_add_u32 s22, s22, 0x100
	s_addc_u32 s23, s23, 0
	s_add_u32 s20, s20, 0x100
	s_addc_u32 s21, s21, 0
	s_cmp_gt_u32 s26, 29
